# orphan SGU units of the sample-GEMM workgroups moved to the end of mix_b; SGU loop-head vmcnt(0) relaxed; scan on all 244 non-GEMM workgroups
# speedup vs baseline: 1.0256x; 1.0086x over previous
.Lsgu_reenter:
	s_mov_b32 s10, s100
	s_mov_b32 s101, 0
.Lsgu_extra:
	s_cmpk_gt_u32 s10, 0x3ff
	s_cbranch_scc1 .LBB0_672
	v_readlane_b32 s0, v253, 63
	s_lshl_b32 s0, s0, 17
	v_readlane_b32 s1, v254, 18
	s_add_u32 s4, s1, s0
	v_readlane_b32 s0, v254, 19
	s_addc_u32 s5, s0, 0
	s_lshl_b32 s0, s10, 7
	s_add_i32 s11, s0, 0xffff0000
	s_branch .LBB0_664
.LBB0_663:
	v_or_b32_e32 v0, s7, v172
	s_add_i32 s0, s8, s43
	v_or_b32_e32 v62, s0, v0
	v_ashrrev_i32_e32 v63, 31, v62
	v_lshl_add_u64 v[62:63], v[62:63], 2, s[66:67]
	global_load_dword v65, v[62:63], off
	s_waitcnt vmcnt(16)
	v_lshlrev_b32_e32 v70, 16, v154
	v_and_b32_e32 v71, 0xffff0000, v154
	v_ashrrev_i32_e32 v171, 31, v170
	v_readlane_b32 s6, v254, 20
	v_lshlrev_b64 v[62:63], 11, v[170:171]
	v_readlane_b32 s7, v254, 21
	s_ashr_i32 s1, s0, 31
	v_ashrrev_i32_e32 v169, 31, v168
	v_lshl_add_u64 v[62:63], s[6:7], 0, v[62:63]
	v_ashrrev_i32_e32 v167, 31, v166
	v_ashrrev_i32_e32 v165, 31, v164
	s_add_i32 s10, s10, s78
	s_waitcnt vmcnt(0)
	v_add_f32_e32 v64, v158, v65
	v_mul_f32_e32 v64, v64, v70
	v_lshlrev_b32_e32 v70, 16, v150
	v_mul_f32_e32 v64, v64, v70
	v_add_f32_e32 v70, v159, v65
	v_mul_f32_e32 v70, v70, v71
	v_and_b32_e32 v71, 0xffff0000, v150
	v_mul_f32_e32 v70, v70, v71
	v_cvt_pk_bf16_f32 v72, v64, v70
	v_add_f32_e32 v64, v160, v65
	v_lshlrev_b32_e32 v70, 16, v155
	v_mul_f32_e32 v64, v64, v70
	v_lshlrev_b32_e32 v70, 16, v151
	v_mul_f32_e32 v64, v64, v70
	v_add_f32_e32 v70, v161, v65
	v_and_b32_e32 v71, 0xffff0000, v155
	v_mul_f32_e32 v70, v70, v71
	v_and_b32_e32 v71, 0xffff0000, v151
	v_mul_f32_e32 v70, v70, v71
	v_cvt_pk_bf16_f32 v73, v64, v70
	v_add_f32_e32 v64, v146, v65
	v_lshlrev_b32_e32 v70, 16, v156
	v_mul_f32_e32 v64, v64, v70
	v_lshlrev_b32_e32 v70, 16, v152
	v_mul_f32_e32 v64, v64, v70
	v_add_f32_e32 v70, v147, v65
	v_and_b32_e32 v71, 0xffff0000, v156
	v_mul_f32_e32 v70, v70, v71
	v_and_b32_e32 v71, 0xffff0000, v152
	v_mul_f32_e32 v70, v70, v71
	v_cvt_pk_bf16_f32 v74, v64, v70
	v_add_f32_e32 v64, v148, v65
	v_lshlrev_b32_e32 v70, 16, v157
	v_mul_f32_e32 v64, v64, v70
	v_lshlrev_b32_e32 v70, 16, v153
	v_mul_f32_e32 v64, v64, v70
	v_add_f32_e32 v70, v149, v65
	v_and_b32_e32 v71, 0xffff0000, v157
	v_mul_f32_e32 v70, v70, v71
	v_and_b32_e32 v71, 0xffff0000, v153
	v_mul_f32_e32 v70, v70, v71
	v_cvt_pk_bf16_f32 v75, v64, v70
	v_lshl_add_u64 v[70:71], v[62:63], 0, v[162:163]
	v_add_f32_e32 v62, v142, v65
	v_lshlrev_b32_e32 v63, 16, v134
	v_mul_f32_e32 v62, v62, v63
	v_lshlrev_b32_e32 v63, 16, v138
	v_mul_f32_e32 v62, v62, v63
	v_add_f32_e32 v63, v143, v65
	v_and_b32_e32 v64, 0xffff0000, v134
	v_mul_f32_e32 v63, v63, v64
	v_and_b32_e32 v64, 0xffff0000, v138
	v_mul_f32_e32 v63, v63, v64
	global_store_dwordx4 v[70:71], v[72:75], off
	v_cvt_pk_bf16_f32 v62, v62, v63
	v_add_f32_e32 v63, v144, v65
	v_lshlrev_b32_e32 v64, 16, v135
	v_mul_f32_e32 v63, v63, v64
	v_lshlrev_b32_e32 v64, 16, v139
	v_mul_f32_e32 v63, v63, v64
	v_add_f32_e32 v64, v145, v65
	v_and_b32_e32 v72, 0xffff0000, v135
	v_mul_f32_e32 v64, v64, v72
	v_and_b32_e32 v72, 0xffff0000, v139
	v_mul_f32_e32 v64, v64, v72
	v_cvt_pk_bf16_f32 v63, v63, v64
	v_add_f32_e32 v64, v130, v65
	v_lshlrev_b32_e32 v72, 16, v136
	v_mul_f32_e32 v64, v64, v72
	v_lshlrev_b32_e32 v72, 16, v140
	v_mul_f32_e32 v64, v64, v72
	v_add_f32_e32 v72, v131, v65
	v_and_b32_e32 v73, 0xffff0000, v136
	v_mul_f32_e32 v72, v72, v73
	v_and_b32_e32 v73, 0xffff0000, v140
	v_mul_f32_e32 v72, v72, v73
	v_cvt_pk_bf16_f32 v64, v64, v72
	v_add_f32_e32 v72, v132, v65
	v_lshlrev_b32_e32 v73, 16, v137
	v_mul_f32_e32 v72, v72, v73
	v_lshlrev_b32_e32 v73, 16, v141
	v_mul_f32_e32 v72, v72, v73
	v_add_f32_e32 v65, v133, v65
	v_and_b32_e32 v73, 0xffff0000, v137
	v_mul_f32_e32 v65, v65, v73
	v_and_b32_e32 v73, 0xffff0000, v141
	v_mul_f32_e32 v65, v65, v73
	v_cvt_pk_bf16_f32 v65, v72, v65
	global_store_dwordx4 v[70:71], v[62:65], off offset:64
	v_lshlrev_b32_e32 v71, 16, v122
	v_and_b32_e32 v72, 0xffff0000, v122
	v_lshl_add_u64 v[62:63], v[0:1], 0, s[0:1]
	v_lshl_add_u64 v[62:63], v[62:63], 2, s[66:67]
	global_load_dword v0, v[62:63], off offset:64
	v_and_b32_e32 v73, 0xffff0000, v123
	v_and_b32_e32 v74, 0xffff0000, v124
	v_lshlrev_b64 v[64:65], 11, v[168:169]
	v_lshl_add_u64 v[64:65], s[6:7], 0, v[64:65]
	v_and_b32_e32 v75, 0xffff0000, v125
	v_lshl_add_u64 v[64:65], v[64:65], 0, v[162:163]
	s_cmp_eq_u32 s100, 0xffffffff
	s_cbranch_scc0 .Lsgu_nx
	s_movk_i32 s10, 0x400

.LBB0_664:
	s_nop 0
	v_mov_b32_e32 v4, v224
	v_mov_b64_e32 v[2:3], s[28:29]
	v_readfirstlane_b32 s12, v4
	s_ashr_i32 s13, s12, 6
	s_and_b32 s14, s13, 1
	s_bitcmp1_b32 s13, 0
	s_cselect_b64 s[8:9], -1, 0
	s_ashr_i32 s6, s12, 7
	v_bfe_u32 v0, v4, 2, 4
	s_ashr_i32 s7, s6, 31
	v_lshl_or_b32 v148, s13, 4, v0
	s_lshl_b64 s[0:1], s[6:7], 7
	s_lshl_b32 s7, s14, 6
	v_add_u32_e32 v0, s11, v148
	s_cmp_eq_u32 s14, 0
	v_mad_i64_i32 v[2:3], s[14:15], v0, s36, v[2:3]
	v_lshlrev_b32_e32 v0, 3, v4
	v_and_b32_e32 v98, 24, v0
	v_lshlrev_b32_e32 v0, 1, v98
	v_lshl_add_u64 v[2:3], v[2:3], 0, v[0:1]
	global_load_dwordx4 v[42:45], v[2:3], off offset:512
	global_load_dwordx4 v[38:41], v[2:3], off offset:576
	global_load_dwordx4 v[66:69], v[2:3], off offset:640
	global_load_dwordx4 v[58:61], v[2:3], off offset:704
	global_load_dwordx4 v[54:57], v[2:3], off offset:768
	global_load_dwordx4 v[34:37], v[2:3], off offset:832
	global_load_dwordx4 v[50:53], v[2:3], off offset:896
	global_load_dwordx4 v[46:49], v[2:3], off offset:960
	v_lshrrev_b32_e32 v2, 1, v4
	v_and_b32_e32 v172, 15, v4
	v_and_b32_e32 v150, 24, v2
	v_or_b32_e32 v62, s0, v172
	v_lshlrev_b32_e32 v2, 1, v150
	v_mov_b32_e32 v3, v1
	v_lshl_add_u64 v[64:65], s[4:5], 0, v[2:3]
	v_or_b32_e32 v2, s7, v62
	v_mov_b32_e32 v3, s1
	v_lshlrev_b64 v[4:5], 8, v[2:3]
	v_or_b32_e32 v6, 16, v2
	v_mov_b32_e32 v7, s1
	v_or_b32_e32 v8, 32, v2
	v_mov_b32_e32 v9, s1
	v_or_b32_e32 v2, 48, v2
	v_lshlrev_b64 v[6:7], 8, v[6:7]
	v_lshlrev_b64 v[8:9], 8, v[8:9]
	v_lshlrev_b64 v[2:3], 8, v[2:3]
	v_lshl_add_u64 v[4:5], v[64:65], 0, v[4:5]
	v_lshl_add_u64 v[6:7], v[64:65], 0, v[6:7]
	v_lshl_add_u64 v[10:11], v[64:65], 0, v[8:9]
	v_lshl_add_u64 v[12:13], v[64:65], 0, v[2:3]
	global_load_dwordx4 v[18:21], v[4:5], off
	global_load_dwordx4 v[26:29], v[6:7], off
	global_load_dwordx4 v[30:33], v[10:11], off
	global_load_dwordx4 v[22:25], v[12:13], off
	global_load_dwordx4 v[14:17], v[4:5], off offset:64
	s_nop 0
	global_load_dwordx4 v[6:9], v[6:7], off offset:64
	s_nop 0
	global_load_dwordx4 v[2:5], v[10:11], off offset:64
	s_nop 0
	global_load_dwordx4 v[10:13], v[12:13], off offset:64
	v_mov_b32_e32 v63, s1
	v_lshlrev_b64 v[62:63], 8, v[62:63]
	v_lshl_add_u64 v[84:85], v[64:65], 0, v[62:63]
	s_cbranch_scc1 .LBB0_666
	v_add_co_u32_e32 v62, vcc, 0x4000, v84
	s_nop 1
	v_addc_co_u32_e32 v63, vcc, 0, v85, vcc
	v_add_co_u32_e32 v64, vcc, 0x5000, v84
	s_nop 1
	v_addc_co_u32_e32 v65, vcc, 0, v85, vcc
	global_load_dwordx4 v[74:77], v[62:63], off offset:128
	global_load_dwordx4 v[78:81], v[64:65], off offset:128
	v_add_co_u32_e32 v62, vcc, 0x6000, v84
	s_nop 1
	v_addc_co_u32_e32 v63, vcc, 0, v85, vcc
	v_add_co_u32_e32 v64, vcc, 0x7000, v84
	s_nop 1
	v_addc_co_u32_e32 v65, vcc, 0, v85, vcc
	global_load_dwordx4 v[90:93], v[62:63], off offset:128
	global_load_dwordx4 v[94:97], v[64:65], off offset:128

.LBB0_672:
	v_readlane_b32 s12, v254, 26
	v_readlane_b32 s13, v254, 27
	s_cmp_eq_u32 s100, 0xffffffff
	s_cbranch_scc1 .Lmixb_back
	s_branch .Lscan_go

.Lscan_go:
	v_readfirstlane_b32 s14, v224
	v_and_b32_e32 v234, 63, v224
	s_lshr_b32 s14, s14, 6
	s_mul_i32 s14, s14, 244
	s_add_i32 s11, s14, s82
	s_sub_i32 s11, s11, 12

.Lsc_next:
	s_add_u32 s11, s11, 1952
	s_branch .Lsc_item

.LBB0_1305:
	s_sub_u32 s0, s82, 232
	s_cmp_lt_u32 s0, 24
	s_cbranch_scc0 .Lmixb_back
	s_add_u32 s10, s0, 0x200
	s_add_u32 s1, s0, 0x2f4
	s_cmp_lt_u32 s0, 12
	s_cselect_b32 s10, s10, s1
	s_mov_b32 s100, 0xffffffff
	s_mov_b32 s101, 0
	s_branch .Lsgu_extra
